# snsa score loop: touch the value row (key row + 512 B) while fetching the key row so the PV loop's row loads hit cache
# baseline (speedup 1.0000x reference)
; DI void snsa_key(const Args& a, int br, int kk, int s, int g, const LAS int* SEL, const int* pt, const float*& kp, const float*& vp, int& dist, bool& valid) {
;     ...
;     if (br == 1) { const int pos = SEL[kk >> 6] * 64 + (kk & 63); dist = PAST - pos; valid = pos <= PAST;
;         if (pos < PAST) { const float* base = INF(a, I_CKV) + ((size_t)pt[pos >> 7] * PAGE + (pos & 127)) * 512; kp = base + 256 + g * 64; vp = base + 384 + g * 64; }
;         else { const float* base = a.out + O_KVS + (size_t)s * 512; kp = base + 256 + g * 64; vp = base + 384 + g * 64; } }
;     else { const int w = kk + 1; dist = 511 - kk;
;         const float* base = w < 512 ? INF(a, I_CWIN) + ((size_t)s * 512 + w) * 256 : a.out + O_WINS + ((size_t)s * 512 + 511) * 256; kp = base + g * 64; vp = base + 128 + g * 64; }
; DI void snsa_unit(const Args& a, LAS unsigned char* lds, int s, int g) {
;     ...
;             for (int u = 0; u < 8; ++u) { const int kk = k0 + 32 * u; const int kc = kk < nkeys ? kk : k0;
;                 if (br == 0) { const u32x2 w = *(const u32x2*)(kcb + (size_t)kc * 64 + 4 * c16); x[u] = (f32x4){bf2f(w.x & 0xffffu), bf2f(w.x >> 16), bf2f(w.y & 0xffffu), bf2f(w.y >> 16)}; dist[u] = 16353 - 16 * kc; valid[u] = true; }
;                 else { const float* kp; const float* vp; snsa_key(a, br, kc, s, g, SEL, pt, kp, vp, dist[u], valid[u]); x[u] = *(const f32x4*)(kp + 4 * c16); if (c16 == 0 && kk < nkeys) VP[kk] = (unsigned long long)(uintptr_t)vp; } }
.LBB0_1472:
	v_lshlrev_b32_e32 v70, 2, v76
	v_lshl_add_u64 v[8:9], v[8:9], 0, v[70:71]
	global_load_dword v131, v[8:9], off offset:512
	global_load_dwordx4 v[38:41], v[8:9], off
	s_mov_b64 s[4:5], exec
	v_readlane_b32 s24, v254, 11
	v_readlane_b32 s25, v254, 12
	s_and_b64 s[24:25], s[4:5], s[24:25]
	s_mov_b64 exec, s[24:25]
	ds_write_b64 v121, v[6:7]
	s_or_b64 exec, exec, s[4:5]
	s_branch .LBB0_1477

; DI void snsa_key(const Args& a, int br, int kk, int s, int g, const LAS int* SEL, const int* pt, const float*& kp, const float*& vp, int& dist, bool& valid) {
;     ...
;     if (br == 1) { const int pos = SEL[kk >> 6] * 64 + (kk & 63); dist = PAST - pos; valid = pos <= PAST;
;         if (pos < PAST) { const float* base = INF(a, I_CKV) + ((size_t)pt[pos >> 7] * PAGE + (pos & 127)) * 512; kp = base + 256 + g * 64; vp = base + 384 + g * 64; }
;         else { const float* base = a.out + O_KVS + (size_t)s * 512; kp = base + 256 + g * 64; vp = base + 384 + g * 64; } }
;     else { const int w = kk + 1; dist = 511 - kk;
;         const float* base = w < 512 ? INF(a, I_CWIN) + ((size_t)s * 512 + w) * 256 : a.out + O_WINS + ((size_t)s * 512 + 511) * 256; kp = base + g * 64; vp = base + 128 + g * 64; }
; DI void snsa_unit(const Args& a, LAS unsigned char* lds, int s, int g) {
;     ...
;             for (int u = 0; u < 8; ++u) { const int kk = k0 + 32 * u; const int kc = kk < nkeys ? kk : k0;
;                 if (br == 0) { const u32x2 w = *(const u32x2*)(kcb + (size_t)kc * 64 + 4 * c16); x[u] = (f32x4){bf2f(w.x & 0xffffu), bf2f(w.x >> 16), bf2f(w.y & 0xffffu), bf2f(w.y >> 16)}; dist[u] = 16353 - 16 * kc; valid[u] = true; }
;                 else { const float* kp; const float* vp; snsa_key(a, br, kc, s, g, SEL, pt, kp, vp, dist[u], valid[u]); x[u] = *(const f32x4*)(kp + 4 * c16); if (c16 == 0 && kk < nkeys) VP[kk] = (unsigned long long)(uintptr_t)vp; } }
.LBB0_1484:
	v_lshlrev_b32_e32 v70, 2, v76
	v_lshl_add_u64 v[42:43], v[42:43], 0, v[70:71]
	global_load_dword v131, v[42:43], off offset:512
	global_load_dwordx4 v[42:45], v[42:43], off
	s_nor_b64 s[28:29], s[6:7], s[28:29]
	s_and_saveexec_b64 s[4:5], s[28:29]
	ds_write_b64 v121, v[48:49] offset:256
	s_or_b64 exec, exec, s[4:5]
	s_mov_b64 s[4:5], 0

; DI void snsa_key(const Args& a, int br, int kk, int s, int g, const LAS int* SEL, const int* pt, const float*& kp, const float*& vp, int& dist, bool& valid) {
;     ...
;     if (br == 1) { const int pos = SEL[kk >> 6] * 64 + (kk & 63); dist = PAST - pos; valid = pos <= PAST;
;         if (pos < PAST) { const float* base = INF(a, I_CKV) + ((size_t)pt[pos >> 7] * PAGE + (pos & 127)) * 512; kp = base + 256 + g * 64; vp = base + 384 + g * 64; }
;         else { const float* base = a.out + O_KVS + (size_t)s * 512; kp = base + 256 + g * 64; vp = base + 384 + g * 64; } }
;     else { const int w = kk + 1; dist = 511 - kk;
;         const float* base = w < 512 ? INF(a, I_CWIN) + ((size_t)s * 512 + w) * 256 : a.out + O_WINS + ((size_t)s * 512 + 511) * 256; kp = base + g * 64; vp = base + 128 + g * 64; }
; DI void snsa_unit(const Args& a, LAS unsigned char* lds, int s, int g) {
;     ...
;             for (int u = 0; u < 8; ++u) { const int kk = k0 + 32 * u; const int kc = kk < nkeys ? kk : k0;
;                 if (br == 0) { const u32x2 w = *(const u32x2*)(kcb + (size_t)kc * 64 + 4 * c16); x[u] = (f32x4){bf2f(w.x & 0xffffu), bf2f(w.x >> 16), bf2f(w.y & 0xffffu), bf2f(w.y >> 16)}; dist[u] = 16353 - 16 * kc; valid[u] = true; }
;                 else { const float* kp; const float* vp; snsa_key(a, br, kc, s, g, SEL, pt, kp, vp, dist[u], valid[u]); x[u] = *(const f32x4*)(kp + 4 * c16); if (c16 == 0 && kk < nkeys) VP[kk] = (unsigned long long)(uintptr_t)vp; } }
.LBB0_1496:
	v_lshlrev_b32_e32 v70, 2, v76
	v_lshl_add_u64 v[46:47], v[46:47], 0, v[70:71]
	global_load_dword v131, v[46:47], off offset:512
	global_load_dwordx4 v[46:49], v[46:47], off
	s_nor_b64 s[66:67], s[6:7], s[28:29]
	s_and_saveexec_b64 s[28:29], s[66:67]
	ds_write_b64 v121, v[52:53] offset:512
	s_or_b64 exec, exec, s[28:29]
	s_mov_b64 s[66:67], 0

; #define LAS __attribute__((address_space(3)))
; DI void snsa_key(const Args& a, int br, int kk, int s, int g, const LAS int* SEL, const int* pt, const float*& kp, const float*& vp, int& dist, bool& valid) {
;     valid = true;
;     if (br == 1) { const int pos = SEL[kk >> 6] * 64 + (kk & 63); dist = PAST - pos; valid = pos <= PAST;
;         if (pos < PAST) { const float* base = INF(a, I_CKV) + ((size_t)pt[pos >> 7] * PAGE + (pos & 127)) * 512; kp = base + 256 + g * 64; vp = base + 384 + g * 64; }
;         else { const float* base = a.out + O_KVS + (size_t)s * 512; kp = base + 256 + g * 64; vp = base + 384 + g * 64; } }
;     else { const int w = kk + 1; dist = 511 - kk;
;         const float* base = w < 512 ? INF(a, I_CWIN) + ((size_t)s * 512 + w) * 256 : a.out + O_WINS + ((size_t)s * 512 + 511) * 256; kp = base + g * 64; vp = base + 128 + g * 64; }
; DI void snsa_unit(const Args& a, LAS unsigned char* lds, int s, int g) {
;     ...
;             for (int u = 0; u < 8; ++u) { const int kk = k0 + 32 * u; const int kc = kk < nkeys ? kk : k0;
;                 if (br == 0) { const u32x2 w = *(const u32x2*)(kcb + (size_t)kc * 64 + 4 * c16); x[u] = (f32x4){bf2f(w.x & 0xffffu), bf2f(w.x >> 16), bf2f(w.y & 0xffffu), bf2f(w.y >> 16)}; dist[u] = 16353 - 16 * kc; valid[u] = true; }
;                 else { const float* kp; const float* vp; snsa_key(a, br, kc, s, g, SEL, pt, kp, vp, dist[u], valid[u]); x[u] = *(const f32x4*)(kp + 4 * c16); if (c16 == 0 && kk < nkeys) VP[kk] = (unsigned long long)(uintptr_t)vp; } }
.LBB0_1508:
	v_lshlrev_b32_e32 v70, 2, v76
	v_lshl_add_u64 v[50:51], v[50:51], 0, v[70:71]
	global_load_dword v131, v[50:51], off offset:512
	global_load_dwordx4 v[50:53], v[50:51], off
	s_nor_b64 s[68:69], s[6:7], s[28:29]
	s_and_saveexec_b64 s[28:29], s[68:69]
	ds_write_b64 v121, v[56:57] offset:768
	s_or_b64 exec, exec, s[28:29]
	s_mov_b64 s[68:69], 0

; #define LAS __attribute__((address_space(3)))
; DI void snsa_key(const Args& a, int br, int kk, int s, int g, const LAS int* SEL, const int* pt, const float*& kp, const float*& vp, int& dist, bool& valid) {
;     valid = true;
;     if (br == 1) { const int pos = SEL[kk >> 6] * 64 + (kk & 63); dist = PAST - pos; valid = pos <= PAST;
;         if (pos < PAST) { const float* base = INF(a, I_CKV) + ((size_t)pt[pos >> 7] * PAGE + (pos & 127)) * 512; kp = base + 256 + g * 64; vp = base + 384 + g * 64; }
;         else { const float* base = a.out + O_KVS + (size_t)s * 512; kp = base + 256 + g * 64; vp = base + 384 + g * 64; } }
;     else { const int w = kk + 1; dist = 511 - kk;
;         const float* base = w < 512 ? INF(a, I_CWIN) + ((size_t)s * 512 + w) * 256 : a.out + O_WINS + ((size_t)s * 512 + 511) * 256; kp = base + g * 64; vp = base + 128 + g * 64; }
; DI void snsa_unit(const Args& a, LAS unsigned char* lds, int s, int g) {
;     ...
;             for (int u = 0; u < 8; ++u) { const int kk = k0 + 32 * u; const int kc = kk < nkeys ? kk : k0;
;                 if (br == 0) { const u32x2 w = *(const u32x2*)(kcb + (size_t)kc * 64 + 4 * c16); x[u] = (f32x4){bf2f(w.x & 0xffffu), bf2f(w.x >> 16), bf2f(w.y & 0xffffu), bf2f(w.y >> 16)}; dist[u] = 16353 - 16 * kc; valid[u] = true; }
;                 else { const float* kp; const float* vp; snsa_key(a, br, kc, s, g, SEL, pt, kp, vp, dist[u], valid[u]); x[u] = *(const f32x4*)(kp + 4 * c16); if (c16 == 0 && kk < nkeys) VP[kk] = (unsigned long long)(uintptr_t)vp; } }
.LBB0_1520:
	v_lshlrev_b32_e32 v70, 2, v76
	v_lshl_add_u64 v[54:55], v[54:55], 0, v[70:71]
	global_load_dword v131, v[54:55], off offset:512
	global_load_dwordx4 v[54:57], v[54:55], off
	s_nor_b64 s[70:71], s[6:7], s[28:29]
	s_and_saveexec_b64 s[28:29], s[70:71]
	ds_write_b64 v121, v[60:61] offset:1024
	s_or_b64 exec, exec, s[28:29]
	s_mov_b64 s[70:71], 0

; #define LAS __attribute__((address_space(3)))
; DI void snsa_key(const Args& a, int br, int kk, int s, int g, const LAS int* SEL, const int* pt, const float*& kp, const float*& vp, int& dist, bool& valid) {
;     valid = true;
;     if (br == 1) { const int pos = SEL[kk >> 6] * 64 + (kk & 63); dist = PAST - pos; valid = pos <= PAST;
;         if (pos < PAST) { const float* base = INF(a, I_CKV) + ((size_t)pt[pos >> 7] * PAGE + (pos & 127)) * 512; kp = base + 256 + g * 64; vp = base + 384 + g * 64; }
;         else { const float* base = a.out + O_KVS + (size_t)s * 512; kp = base + 256 + g * 64; vp = base + 384 + g * 64; } }
;     else { const int w = kk + 1; dist = 511 - kk;
;         const float* base = w < 512 ? INF(a, I_CWIN) + ((size_t)s * 512 + w) * 256 : a.out + O_WINS + ((size_t)s * 512 + 511) * 256; kp = base + g * 64; vp = base + 128 + g * 64; }
; DI void snsa_unit(const Args& a, LAS unsigned char* lds, int s, int g) {
;     ...
;             for (int u = 0; u < 8; ++u) { const int kk = k0 + 32 * u; const int kc = kk < nkeys ? kk : k0;
;                 if (br == 0) { const u32x2 w = *(const u32x2*)(kcb + (size_t)kc * 64 + 4 * c16); x[u] = (f32x4){bf2f(w.x & 0xffffu), bf2f(w.x >> 16), bf2f(w.y & 0xffffu), bf2f(w.y >> 16)}; dist[u] = 16353 - 16 * kc; valid[u] = true; }
;                 else { const float* kp; const float* vp; snsa_key(a, br, kc, s, g, SEL, pt, kp, vp, dist[u], valid[u]); x[u] = *(const f32x4*)(kp + 4 * c16); if (c16 == 0 && kk < nkeys) VP[kk] = (unsigned long long)(uintptr_t)vp; } }
.LBB0_1532:
	v_lshlrev_b32_e32 v70, 2, v76
	v_lshl_add_u64 v[58:59], v[58:59], 0, v[70:71]
	global_load_dword v131, v[58:59], off offset:512
	global_load_dwordx4 v[58:61], v[58:59], off
	s_nor_b64 s[78:79], s[6:7], s[28:29]
	s_and_saveexec_b64 s[28:29], s[78:79]
	ds_write_b64 v121, v[64:65] offset:1280
	s_or_b64 exec, exec, s[28:29]
	s_mov_b64 s[78:79], 0

; #define LAS __attribute__((address_space(3)))
; DI void snsa_key(const Args& a, int br, int kk, int s, int g, const LAS int* SEL, const int* pt, const float*& kp, const float*& vp, int& dist, bool& valid) {
;     valid = true;
;     if (br == 1) { const int pos = SEL[kk >> 6] * 64 + (kk & 63); dist = PAST - pos; valid = pos <= PAST;
;         if (pos < PAST) { const float* base = INF(a, I_CKV) + ((size_t)pt[pos >> 7] * PAGE + (pos & 127)) * 512; kp = base + 256 + g * 64; vp = base + 384 + g * 64; }
;         else { const float* base = a.out + O_KVS + (size_t)s * 512; kp = base + 256 + g * 64; vp = base + 384 + g * 64; } }
;     else { const int w = kk + 1; dist = 511 - kk;
;         const float* base = w < 512 ? INF(a, I_CWIN) + ((size_t)s * 512 + w) * 256 : a.out + O_WINS + ((size_t)s * 512 + 511) * 256; kp = base + g * 64; vp = base + 128 + g * 64; }
; DI void snsa_unit(const Args& a, LAS unsigned char* lds, int s, int g) {
;     ...
;             for (int u = 0; u < 8; ++u) { const int kk = k0 + 32 * u; const int kc = kk < nkeys ? kk : k0;
;                 if (br == 0) { const u32x2 w = *(const u32x2*)(kcb + (size_t)kc * 64 + 4 * c16); x[u] = (f32x4){bf2f(w.x & 0xffffu), bf2f(w.x >> 16), bf2f(w.y & 0xffffu), bf2f(w.y >> 16)}; dist[u] = 16353 - 16 * kc; valid[u] = true; }
;                 else { const float* kp; const float* vp; snsa_key(a, br, kc, s, g, SEL, pt, kp, vp, dist[u], valid[u]); x[u] = *(const f32x4*)(kp + 4 * c16); if (c16 == 0 && kk < nkeys) VP[kk] = (unsigned long long)(uintptr_t)vp; } }
.LBB0_1544:
	v_lshlrev_b32_e32 v70, 2, v76
	v_lshl_add_u64 v[62:63], v[62:63], 0, v[70:71]
	global_load_dword v131, v[62:63], off offset:512
	global_load_dwordx4 v[62:65], v[62:63], off
	s_nor_b64 s[82:83], s[6:7], s[28:29]
	s_and_saveexec_b64 s[28:29], s[82:83]
	ds_write_b64 v121, v[68:69] offset:1536
	s_or_b64 exec, exec, s[28:29]
	s_mov_b64 s[82:83], 0

; #define LAS __attribute__((address_space(3)))
; DI void snsa_key(const Args& a, int br, int kk, int s, int g, const LAS int* SEL, const int* pt, const float*& kp, const float*& vp, int& dist, bool& valid) {
;     valid = true;
;     if (br == 1) { const int pos = SEL[kk >> 6] * 64 + (kk & 63); dist = PAST - pos; valid = pos <= PAST;
;         if (pos < PAST) { const float* base = INF(a, I_CKV) + ((size_t)pt[pos >> 7] * PAGE + (pos & 127)) * 512; kp = base + 256 + g * 64; vp = base + 384 + g * 64; }
;         else { const float* base = a.out + O_KVS + (size_t)s * 512; kp = base + 256 + g * 64; vp = base + 384 + g * 64; } }
;     else { const int w = kk + 1; dist = 511 - kk;
;         const float* base = w < 512 ? INF(a, I_CWIN) + ((size_t)s * 512 + w) * 256 : a.out + O_WINS + ((size_t)s * 512 + 511) * 256; kp = base + g * 64; vp = base + 128 + g * 64; }
; DI void snsa_unit(const Args& a, LAS unsigned char* lds, int s, int g) {
;     ...
;             for (int u = 0; u < 8; ++u) { const int kk = k0 + 32 * u; const int kc = kk < nkeys ? kk : k0;
;                 if (br == 0) { const u32x2 w = *(const u32x2*)(kcb + (size_t)kc * 64 + 4 * c16); x[u] = (f32x4){bf2f(w.x & 0xffffu), bf2f(w.x >> 16), bf2f(w.y & 0xffffu), bf2f(w.y >> 16)}; dist[u] = 16353 - 16 * kc; valid[u] = true; }
;                 else { const float* kp; const float* vp; snsa_key(a, br, kc, s, g, SEL, pt, kp, vp, dist[u], valid[u]); x[u] = *(const f32x4*)(kp + 4 * c16); if (c16 == 0 && kk < nkeys) VP[kk] = (unsigned long long)(uintptr_t)vp; } }
.LBB0_1556:
	v_lshlrev_b32_e32 v70, 2, v76
	v_lshl_add_u64 v[66:67], v[66:67], 0, v[70:71]
	global_load_dword v131, v[66:67], off offset:512
	global_load_dwordx4 v[66:69], v[66:67], off
	s_nor_b64 s[28:29], s[6:7], s[28:29]
	s_and_saveexec_b64 s[24:25], s[28:29]
	ds_write_b64 v121, v[94:95] offset:1792
	s_or_b64 exec, exec, s[24:25]
	s_mov_b64 s[82:83], 0
